# mixer_post loop-top vmcnt(0) removed; N2 norm_rows: g hoisted out of row loop, x6/x7 + scale/shift loads issued before the x waits
# baseline (speedup 1.0000x reference)
; #define p (kparams())
; __device__ __forceinline__ void mixer_post(const int wv_, KPR p, int l) {
;     ...
;   for (int row = blockIdx.x * 8 + wid; row < T; row += gridDim.x * 8) {
;     const bf16_t* pr = PNG + (size_t)row * NNGP;
;     {
;       float a[8], bq[8], v[8], g[8], y[8];
;       ld8(pr + c0, a); ld8(pr + 512 + c0, bq); ldh8(PRE + AE + (size_t)row * 512 + c0, v); ldh8(PRE + 9 * AE + (size_t)row * 512 + c0, g);
;       float sm = 0.f;
; #pragma unroll
;       for (int e = 0; e < 8; ++e) { y[e] = a[e] + bq[e]; sm += y[e]; }
;       const float mean = group_sum(sm, 8) * (1.f / 64.f);
;       float sq = 0.f;
; #pragma unroll
;       for (int e = 0; e < 8; ++e) { y[e] -= mean; sq += y[e] * y[e]; }
;       const float rstd = rsqrtf(group_sum(sq, 8) * (1.f / 64.f) + 64e-5f);
;       const float rk = RK[(size_t)row * 8 + (lane >> 3)];
; #pragma unroll
;       for (int e = 0; e < 8; ++e) { const int c = c0 + e; y[e] = (y[e] * rstd * p->in[I_RWLNW][l * C + c] + p->in[I_RWLNB][l * C + c] + rk * v[e]) * g[e]; }
;       st8(Y + (size_t)row * 512 + c0, y); }
.LBB0_743:
	v_mad_i64_i32 v[70:71], s[8:9], v0, s81, v[48:49]
	global_load_dwordx4 v[52:55], v[70:71], off
	global_load_dwordx4 v[60:63], v[70:71], off offset:1024
	v_ashrrev_i32_e32 v1, 31, v0
	v_lshlrev_b64 v[56:57], 10, v[0:1]
	v_lshl_add_u64 v[4:5], v[24:25], 0, v[56:57]
	global_load_dwordx4 v[12:15], v[4:5], off
	v_lshl_add_u64 v[4:5], v[26:27], 0, v[56:57]
	v_add_co_u32_e32 v20, vcc, s52, v70
	global_load_dwordx4 v[8:11], v[4:5], off
	v_lshl_add_u64 v[4:5], v[36:37], 0, v[56:57]
	v_lshl_add_u64 v[6:7], v[38:39], 0, v[56:57]
	v_addc_co_u32_e32 v21, vcc, 0, v71, vcc
	global_load_dwordx4 v[16:19], v[4:5], off
	s_nop 0
	global_load_dwordx4 v[4:7], v[6:7], off
	v_lshlrev_b64 v[50:51], 5, v[0:1]
	global_load_dwordx4 v[20:23], v[20:21], off offset:3840
	v_lshl_add_u64 v[50:51], v[28:29], 0, v[50:51]
	global_load_dword v58, v[50:51], off
	global_load_dwordx4 v[64:67], v[32:33], off offset:16
	global_load_dwordx4 v[72:75], v[32:33], off
	global_load_dwordx4 v[76:79], v[34:35], off offset:16
	global_load_dwordx4 v[80:83], v[34:35], off
	v_lshl_add_u64 v[50:51], v[30:31], 0, v[56:57]
	v_lshl_add_u64 v[68:69], v[42:43], 0, v[56:57]
	v_lshl_add_u64 v[56:57], v[44:45], 0, v[56:57]
	global_load_dwordx4 v[84:87], v[68:69], off
	global_load_dwordx4 v[88:91], v[56:57], off
	s_brev_b32 s8, 60
	v_add_u32_e32 v0, s73, v0
	s_waitcnt vmcnt(13)
	v_lshlrev_b32_e32 v56, 16, v55
	v_and_b32_e32 v57, 0xffff0000, v55
	s_waitcnt vmcnt(12)
	v_lshlrev_b32_e32 v68, 16, v63
	v_and_b32_e32 v69, 0xffff0000, v63
	v_lshlrev_b32_e32 v92, 16, v54
	v_and_b32_e32 v93, 0xffff0000, v54
	v_lshlrev_b32_e32 v54, 16, v62
	v_and_b32_e32 v55, 0xffff0000, v62
	v_lshlrev_b32_e32 v62, 16, v53
	v_and_b32_e32 v63, 0xffff0000, v53
	v_lshlrev_b32_e32 v94, 16, v61
	v_and_b32_e32 v95, 0xffff0000, v61
	v_lshlrev_b32_e32 v96, 16, v52
	v_and_b32_e32 v97, 0xffff0000, v52
	v_lshlrev_b32_e32 v52, 16, v60
	v_and_b32_e32 v53, 0xffff0000, v60
	v_pk_add_f32 v[60:61], v[62:63], v[94:95]
	v_pk_add_f32 v[62:63], v[96:97], v[52:53]
	v_pk_add_f32 v[54:55], v[92:93], v[54:55]
	v_add_f32_e32 v1, 0, v62
	v_add_f32_e32 v1, v63, v1
	v_add_f32_e32 v1, v60, v1
	v_add_f32_e32 v1, v61, v1
	v_add_f32_e32 v1, v54, v1
	v_pk_add_f32 v[56:57], v[56:57], v[68:69]
	v_add_f32_e32 v1, v55, v1
	v_add_f32_e32 v1, v56, v1
	v_add_f32_e32 v1, v57, v1
	ds_bpermute_b32 v3, v170, v1
	s_waitcnt vmcnt(11)
	v_cvt_f32_f16_e32 v68, v15
	v_cvt_f32_f16_sdwa v69, v15 dst_sel:DWORD dst_unused:UNUSED_PAD src0_sel:WORD_1
	s_waitcnt vmcnt(10)
	v_cvt_f32_f16_e32 v92, v11
	v_cvt_f32_f16_sdwa v93, v11 dst_sel:DWORD dst_unused:UNUSED_PAD src0_sel:WORD_1
	s_waitcnt lgkmcnt(0)
	v_add_f32_e32 v1, v1, v3
	ds_bpermute_b32 v3, v171, v1
	v_cvt_f32_f16_e32 v94, v14
	v_cvt_f32_f16_sdwa v95, v14 dst_sel:DWORD dst_unused:UNUSED_PAD src0_sel:WORD_1
	v_cvt_f32_f16_e32 v14, v10
	v_cvt_f32_f16_sdwa v15, v10 dst_sel:DWORD dst_unused:UNUSED_PAD src0_sel:WORD_1
	s_waitcnt lgkmcnt(0)
	v_add_f32_e32 v1, v1, v3
	ds_bpermute_b32 v3, v172, v1
	v_cvt_f32_f16_e32 v10, v13
	v_cvt_f32_f16_sdwa v11, v13 dst_sel:DWORD dst_unused:UNUSED_PAD src0_sel:WORD_1
	v_cvt_f32_f16_e32 v96, v9
	v_cvt_f32_f16_sdwa v97, v9 dst_sel:DWORD dst_unused:UNUSED_PAD src0_sel:WORD_1
	s_waitcnt lgkmcnt(0)
	v_add_f32_e32 v1, v1, v3
	v_mul_f32_e32 v102, 0x3c800000, v1
	v_pk_add_f32 v[62:63], v[62:63], v[102:103] op_sel_hi:[1,0] neg_lo:[0,1] neg_hi:[0,1]
	v_pk_add_f32 v[60:61], v[60:61], v[102:103] op_sel_hi:[1,0] neg_lo:[0,1] neg_hi:[0,1]
	v_pk_add_f32 v[104:105], v[54:55], v[102:103] op_sel_hi:[1,0] neg_lo:[0,1] neg_hi:[0,1]
	v_pk_mul_f32 v[54:55], v[62:63], v[62:63]
	v_pk_add_f32 v[102:103], v[56:57], v[102:103] op_sel_hi:[1,0] neg_lo:[0,1] neg_hi:[0,1]
	v_pk_mul_f32 v[56:57], v[60:61], v[60:61]
	v_add_f32_e32 v1, v54, v55
	v_add_f32_e32 v1, v56, v1
	v_pk_mul_f32 v[106:107], v[104:105], v[104:105]
	v_add_f32_e32 v1, v57, v1
	v_add_f32_e32 v1, v106, v1
	v_pk_mul_f32 v[108:109], v[102:103], v[102:103]
	v_add_f32_e32 v1, v107, v1
	v_add_f32_e32 v1, v108, v1
	v_add_f32_e32 v1, v109, v1
	ds_bpermute_b32 v3, v170, v1
	s_waitcnt vmcnt(7)
	v_lshlrev_b32_e32 v106, 16, v22
	v_cvt_f32_f16_e32 v98, v12
	v_cvt_f32_f16_sdwa v99, v12 dst_sel:DWORD dst_unused:UNUSED_PAD src0_sel:WORD_1
	v_cvt_f32_f16_e32 v12, v8
	s_waitcnt lgkmcnt(0)
	v_add_f32_e32 v1, v1, v3
	ds_bpermute_b32 v3, v171, v1
	v_cvt_f32_f16_sdwa v13, v8 dst_sel:DWORD dst_unused:UNUSED_PAD src0_sel:WORD_1
	v_lshlrev_b32_e32 v8, 16, v19
	v_and_b32_e32 v9, 0xffff0000, v19
	v_lshlrev_b32_e32 v56, 16, v18
	s_waitcnt lgkmcnt(0)
	v_add_f32_e32 v1, v1, v3
	ds_bpermute_b32 v3, v172, v1
	v_and_b32_e32 v57, 0xffff0000, v18
	v_lshlrev_b32_e32 v18, 16, v6
	v_and_b32_e32 v19, 0xffff0000, v6
	v_mul_f32_e32 v6, 0xbfb8aa3b, v106
	s_waitcnt lgkmcnt(0)
	v_add_f32_e32 v1, v1, v3
	v_fmamk_f32 v1, v1, 0x3c800000, v180
	v_mul_f32_e32 v3, 0x4b800000, v1
	v_cmp_gt_f32_e32 vcc, s96, v1
	v_exp_f32_e32 v6, v6
	v_and_b32_e32 v107, 0xffff0000, v22
	v_cndmask_b32_e32 v1, v1, v3, vcc
	v_rsq_f32_e32 v1, v1
	v_add_f32_e32 v6, 1.0, v6
	v_pk_add_f32 v[56:57], v[56:57], v[18:19]
	v_rcp_f32_e32 v18, v6
	v_mul_f32_e32 v6, 0x45800000, v1
	v_lshlrev_b32_e32 v100, 16, v7
	v_and_b32_e32 v101, 0xffff0000, v7
	v_mul_f32_e32 v7, 0xbfb8aa3b, v107
	v_cndmask_b32_e32 v6, v1, v6, vcc
	v_lshlrev_b32_e32 v52, 16, v23
	v_and_b32_e32 v53, 0xffff0000, v23
	v_pk_add_f32 v[54:55], v[8:9], v[100:101]
	v_exp_f32_e32 v3, v7
	v_pk_mul_f32 v[8:9], v[62:63], v[6:7] op_sel_hi:[1,0]
	v_pk_mul_f32 v[22:23], v[60:61], v[6:7] op_sel_hi:[1,0]
	v_pk_mul_f32 v[60:61], v[104:105], v[6:7] op_sel_hi:[1,0]
	v_pk_mul_f32 v[6:7], v[102:103], v[6:7] op_sel_hi:[1,0]
	s_waitcnt vmcnt(2)
; __device__ __forceinline__ float sigm(float x) { return __builtin_amdgcn_rcpf(1.f + __expf(-x)); }
; #define p (kparams())
; __device__ __forceinline__ void mixer_post(const int wv_, KPR p, int l) {
;     ...
; #pragma unroll
;       for (int e = 0; e < 8; ++e) { const int c = c0 + e; y[e] = (y[e] * rstd * p->in[I_RWLNW][l * C + c] + p->in[I_RWLNB][l * C + c] + rk * v[e]) * g[e]; }
;       st8(Y + (size_t)row * 512 + c0, y); }
; #pragma unroll
;     for (int mx = 0; mx < 2; ++mx) {
;       const bf16_t* O = mx == 0 ? OH : OG; const float* nw = (mx == 0 ? p->in[I_HGNORM] : p->in[I_GLANORM]) + l * C;
;       float a[8], bq[8], gt[8], y[8];
;       ld8(O + (size_t)row * 512 + c0, a); ld8(O + AE + (size_t)row * 512 + c0, bq); ld8(pr + (mx == 0 ? O_HG : O_GG) + c0, gt);
;       float sq = 0.f;
; #pragma unroll
;       for (int e = 0; e < 8; ++e) { y[e] = a[e] + bq[e]; sq += y[e] * y[e]; }
;       const float rstd = rsqrtf(group_sum(sq, 16) * (1.f / 128.f) + 1e-6f);
; #pragma unroll
;       for (int e = 0; e < 8; ++e) y[e] = y[e] * rstd * nw[c0 + e] * (gt[e] * sigm(gt[e]));
;       st8(Y + (size_t)(1 + mx) * AE + (size_t)row * 512 + c0, y); }
	v_pk_fma_f32 v[8:9], v[72:73], v[8:9], v[80:81]
	v_pk_fma_f32 v[22:23], v[74:75], v[22:23], v[82:83]
	v_pk_fma_f32 v[60:61], v[64:65], v[60:61], v[76:77]
	v_pk_fma_f32 v[6:7], v[66:67], v[6:7], v[78:79]
	v_pk_fma_f32 v[8:9], v[58:59], v[98:99], v[8:9] op_sel_hi:[0,1,1]
	v_pk_fma_f32 v[10:11], v[58:59], v[10:11], v[22:23] op_sel_hi:[0,1,1]
	v_pk_fma_f32 v[22:23], v[58:59], v[94:95], v[60:61] op_sel_hi:[0,1,1]
	v_pk_fma_f32 v[6:7], v[58:59], v[68:69], v[6:7] op_sel_hi:[0,1,1]
	v_pk_mul_f32 v[8:9], v[8:9], v[12:13]
	v_pk_mul_f32 v[10:11], v[10:11], v[96:97]
	v_pk_mul_f32 v[12:13], v[22:23], v[14:15]
	v_pk_mul_f32 v[14:15], v[6:7], v[92:93]
	v_cvt_pk_bf16_f32 v6, v8, v9
	v_cvt_pk_bf16_f32 v7, v10, v11
	v_cvt_pk_bf16_f32 v8, v12, v13
	v_cvt_pk_bf16_f32 v9, v14, v15
	global_store_dwordx4 v[50:51], v[6:9], off
	global_load_dwordx4 v[8:11], v[40:41], off offset:16
	s_nop 0
	global_load_dwordx4 v[12:15], v[40:41], off
	v_add_f32_e32 v1, 1.0, v3
	v_rcp_f32_e32 v19, v1
	v_lshlrev_b32_e32 v22, 16, v5
	v_and_b32_e32 v23, 0xffff0000, v5
	v_lshlrev_b32_e32 v62, 16, v21
	v_pk_mul_f32 v[58:59], v[18:19], v[106:107]
	v_lshlrev_b32_e32 v18, 16, v17
	v_and_b32_e32 v19, 0xffff0000, v17
	v_pk_add_f32 v[60:61], v[18:19], v[22:23]
	v_lshlrev_b32_e32 v18, 16, v16
	v_and_b32_e32 v19, 0xffff0000, v16
	v_lshlrev_b32_e32 v16, 16, v4
	v_and_b32_e32 v17, 0xffff0000, v4
	v_and_b32_e32 v63, 0xffff0000, v21
	v_lshlrev_b32_e32 v68, 16, v20
	v_and_b32_e32 v69, 0xffff0000, v20
	v_pk_add_f32 v[66:67], v[18:19], v[16:17]
	s_waitcnt vmcnt(4)
	v_lshlrev_b32_e32 v18, 16, v86
	v_and_b32_e32 v19, 0xffff0000, v86
	s_waitcnt vmcnt(3)
	v_lshlrev_b32_e32 v20, 16, v90
	v_and_b32_e32 v21, 0xffff0000, v90
	v_pk_add_f32 v[18:19], v[18:19], v[20:21]
	v_lshlrev_b32_e32 v20, 16, v85
	v_and_b32_e32 v21, 0xffff0000, v85
	v_lshlrev_b32_e32 v22, 16, v89
	v_and_b32_e32 v23, 0xffff0000, v89
	v_pk_add_f32 v[20:21], v[20:21], v[22:23]
	v_lshlrev_b32_e32 v22, 16, v84
	v_and_b32_e32 v23, 0xffff0000, v84
	v_lshlrev_b32_e32 v78, 16, v88
	v_and_b32_e32 v79, 0xffff0000, v88
	v_pk_add_f32 v[22:23], v[22:23], v[78:79]
	v_mov_b32_e32 v81, v67
	v_mov_b32_e32 v80, v23
	v_pk_mul_f32 v[72:73], v[60:61], v[60:61]
	v_pk_mul_f32 v[76:77], v[20:21], v[20:21]
	v_mov_b32_e32 v78, v22
	v_mov_b32_e32 v79, v66
	v_pk_mul_f32 v[80:81], v[80:81], v[80:81]
	v_pk_mul_f32 v[6:7], v[56:57], v[56:57]
	v_pk_fma_f32 v[78:79], v[78:79], v[78:79], v[80:81]
	v_mov_b32_e32 v80, v76
	v_mov_b32_e32 v81, v72
	v_lshlrev_b32_e32 v4, 16, v87
	v_and_b32_e32 v5, 0xffff0000, v87
	v_lshlrev_b32_e32 v16, 16, v91
	v_and_b32_e32 v17, 0xffff0000, v91
	v_pk_mul_f32 v[74:75], v[18:19], v[18:19]
	v_pk_add_f32 v[78:79], v[80:81], v[78:79]
	v_mov_b32_e32 v72, v77
	v_pk_add_f32 v[16:17], v[4:5], v[16:17]
	v_pk_add_f32 v[72:73], v[72:73], v[78:79]
	v_mov_b32_e32 v76, v74
	v_mov_b32_e32 v77, v6
	v_pk_mul_f32 v[100:101], v[54:55], v[54:55]
	v_pk_mul_f32 v[4:5], v[16:17], v[16:17]
	v_pk_add_f32 v[72:73], v[76:77], v[72:73]
	v_mov_b32_e32 v6, v75
	v_pk_add_f32 v[6:7], v[6:7], v[72:73]
	v_mov_b32_e32 v72, v4
	v_mov_b32_e32 v73, v100
	v_pk_add_f32 v[6:7], v[72:73], v[6:7]
	v_mov_b32_e32 v100, v5
	v_pk_add_f32 v[4:5], v[100:101], v[6:7]
	ds_bpermute_b32 v7, v170, v5
	ds_bpermute_b32 v6, v170, v4
	v_mul_f32_e32 v1, 0xbfb8aa3b, v62
	v_exp_f32_e32 v1, v1
	v_mul_f32_e32 v3, 0xbfb8aa3b, v63
	v_exp_f32_e32 v3, v3
	s_waitcnt lgkmcnt(0)
	v_pk_add_f32 v[4:5], v[4:5], v[6:7]
	ds_bpermute_b32 v7, v171, v5
	ds_bpermute_b32 v6, v171, v4
	v_add_f32_e32 v1, 1.0, v1
	v_rcp_f32_e32 v64, v1
	v_add_f32_e32 v1, 1.0, v3
	v_rcp_f32_e32 v65, v1
	v_mul_f32_e32 v1, 0xbfb8aa3b, v68
	v_exp_f32_e32 v1, v1
	s_waitcnt lgkmcnt(0)
	v_pk_add_f32 v[74:75], v[4:5], v[6:7]
	v_add_co_u32_e32 v4, vcc, s63, v70
	v_add_f32_e32 v1, 1.0, v1
	s_nop 0
	v_addc_co_u32_e32 v5, vcc, 0, v71, vcc
	global_load_dwordx4 v[4:7], v[4:5], off offset:2880
	v_rcp_f32_e32 v72, v1
	v_mul_f32_e32 v1, 0xbfb8aa3b, v69
	ds_bpermute_b32 v77, v172, v75
	ds_bpermute_b32 v76, v172, v74
	v_exp_f32_e32 v1, v1
	v_mul_f32_e32 v3, 0xbfb8aa3b, v53
	v_exp_f32_e32 v3, v3
	v_pk_mul_f32 v[62:63], v[64:65], v[62:63]
	v_add_f32_e32 v1, 1.0, v1
	s_waitcnt lgkmcnt(0)
; __device__ __forceinline__ float sigm(float x) { return __builtin_amdgcn_rcpf(1.f + __expf(-x)); }
; #define p (kparams())
; __device__ __forceinline__ void mixer_post(const int wv_, KPR p, int l) {
;     ...
;     for (int mx = 0; mx < 2; ++mx) {
;       const bf16_t* O = mx == 0 ? OH : OG; const float* nw = (mx == 0 ? p->in[I_HGNORM] : p->in[I_GLANORM]) + l * C;
;       float a[8], bq[8], gt[8], y[8];
;       ld8(O + (size_t)row * 512 + c0, a); ld8(O + AE + (size_t)row * 512 + c0, bq); ld8(pr + (mx == 0 ? O_HG : O_GG) + c0, gt);
;       float sq = 0.f;
; #pragma unroll
;       for (int e = 0; e < 8; ++e) { y[e] = a[e] + bq[e]; sq += y[e] * y[e]; }
;       const float rstd = rsqrtf(group_sum(sq, 16) * (1.f / 128.f) + 1e-6f);
; #pragma unroll
;       for (int e = 0; e < 8; ++e) y[e] = y[e] * rstd * nw[c0 + e] * (gt[e] * sigm(gt[e]));
;       st8(Y + (size_t)(1 + mx) * AE + (size_t)row * 512 + c0, y); }
	v_pk_add_f32 v[70:71], v[74:75], v[76:77]
	v_rcp_f32_e32 v73, v1
	v_mul_f32_e32 v1, 0xbfb8aa3b, v52
	ds_bpermute_b32 v77, v173, v71
	ds_bpermute_b32 v76, v173, v70
	v_exp_f32_e32 v1, v1
	v_pk_mul_f32 v[64:65], v[72:73], v[68:69]
	v_add_f32_e32 v1, 1.0, v1
	s_waitcnt lgkmcnt(0)
	v_pk_add_f32 v[70:71], v[70:71], v[76:77]
	v_rcp_f32_e32 v74, v1
	v_add_f32_e32 v1, 1.0, v3
	v_pk_fma_f32 v[70:71], v[70:71], s[8:9], v[152:153] op_sel_hi:[1,0,0]
	v_rcp_f32_e32 v75, v1
	v_mul_f32_e32 v1, 0x4b800000, v71
	v_cmp_gt_f32_e32 vcc, s96, v71
	v_pk_mul_f32 v[52:53], v[74:75], v[52:53]
	s_nop 0
	v_cndmask_b32_e32 v1, v71, v1, vcc
	v_rsq_f32_e32 v1, v1
	s_nop 0
	v_mul_f32_e32 v3, 0x45800000, v1
	v_cndmask_b32_e32 v68, v1, v3, vcc
	v_pk_mul_f32 v[56:57], v[56:57], v[68:69] op_sel_hi:[1,0]
	v_pk_mul_f32 v[66:67], v[66:67], v[68:69] op_sel_hi:[1,0]
	s_waitcnt vmcnt(2)
	v_pk_mul_f32 v[8:9], v[8:9], v[56:57]
	s_waitcnt vmcnt(1)
	v_pk_mul_f32 v[12:13], v[12:13], v[66:67]
	v_pk_mul_f32 v[60:61], v[60:61], v[68:69] op_sel_hi:[1,0]
	v_pk_mul_f32 v[56:57], v[58:59], v[8:9]
	v_pk_mul_f32 v[8:9], v[54:55], v[68:69] op_sel_hi:[1,0]
	v_pk_mul_f32 v[12:13], v[64:65], v[12:13]
	v_pk_mul_f32 v[14:15], v[14:15], v[60:61]
	v_pk_mul_f32 v[8:9], v[10:11], v[8:9]
	v_pk_mul_f32 v[14:15], v[62:63], v[14:15]
	v_pk_mul_f32 v[52:53], v[52:53], v[8:9]
	v_cvt_pk_bf16_f32 v8, v12, v13
	v_add_co_u32_e32 v12, vcc, s55, v50
	v_cvt_pk_bf16_f32 v9, v14, v15
	v_cvt_pk_bf16_f32 v10, v56, v57
	v_cvt_pk_bf16_f32 v11, v52, v53
	v_addc_co_u32_e32 v13, vcc, 0, v51, vcc
	global_store_dwordx4 v[12:13], v[8:11], off
	global_load_dwordx4 v[8:11], v[46:47], off
	s_nop 0
	global_load_dwordx4 v[12:15], v[46:47], off offset:16
	v_cmp_gt_f32_e32 vcc, s96, v70
	s_waitcnt vmcnt(3)
	v_lshlrev_b32_e32 v54, 16, v6
	v_and_b32_e32 v55, 0xffff0000, v6
	v_mul_f32_e32 v1, 0xbfb8aa3b, v54
	v_exp_f32_e32 v1, v1
	v_mul_f32_e32 v3, 0xbfb8aa3b, v55
	v_exp_f32_e32 v3, v3
	v_lshlrev_b32_e32 v56, 16, v5
	v_add_f32_e32 v1, 1.0, v1
	v_rcp_f32_e32 v6, v1
	v_add_f32_e32 v1, 1.0, v3
	v_mul_f32_e32 v3, 0xbfb8aa3b, v56
	v_and_b32_e32 v57, 0xffff0000, v5
	v_exp_f32_e32 v3, v3
	v_mul_f32_e32 v5, 0xbfb8aa3b, v57
	v_exp_f32_e32 v5, v5
	v_lshlrev_b32_e32 v60, 16, v4
	v_lshlrev_b32_e32 v52, 16, v7
	v_and_b32_e32 v53, 0xffff0000, v7
	v_rcp_f32_e32 v7, v1
	v_add_f32_e32 v1, 1.0, v3
	v_and_b32_e32 v61, 0xffff0000, v4
	v_mul_f32_e32 v3, 0xbfb8aa3b, v60
	v_exp_f32_e32 v3, v3
	v_mul_f32_e32 v4, 0xbfb8aa3b, v61
	v_rcp_f32_e32 v58, v1
	v_add_f32_e32 v1, 1.0, v5
	v_exp_f32_e32 v5, v4
	v_rcp_f32_e32 v59, v1
	v_add_f32_e32 v1, 1.0, v3
	v_rcp_f32_e32 v4, v1
	v_add_f32_e32 v1, 1.0, v5
	v_rcp_f32_e32 v5, v1
	v_mul_f32_e32 v1, 0x4b800000, v70
	v_cndmask_b32_e32 v1, v70, v1, vcc
	v_rsq_f32_e32 v1, v1
	v_pk_mul_f32 v[6:7], v[6:7], v[54:55]
	v_pk_mul_f32 v[54:55], v[58:59], v[56:57]
	v_pk_mul_f32 v[4:5], v[4:5], v[60:61]
	v_mul_f32_e32 v3, 0x45800000, v1
	v_cndmask_b32_e32 v56, v1, v3, vcc
	v_mul_f32_e32 v1, 0xbfb8aa3b, v52
	v_exp_f32_e32 v1, v1
	v_mul_f32_e32 v3, 0xbfb8aa3b, v53
	v_pk_mul_f32 v[22:23], v[22:23], v[56:57] op_sel_hi:[1,0]
	v_exp_f32_e32 v3, v3
	v_add_f32_e32 v1, 1.0, v1
	s_waitcnt vmcnt(1)
	v_pk_mul_f32 v[8:9], v[8:9], v[22:23]
	s_nop 0
	v_pk_mul_f32 v[4:5], v[4:5], v[8:9]
	v_pk_mul_f32 v[8:9], v[20:21], v[56:57] op_sel_hi:[1,0]
	v_cvt_pk_bf16_f32 v4, v4, v5
	v_pk_mul_f32 v[8:9], v[10:11], v[8:9]
	v_pk_mul_f32 v[10:11], v[18:19], v[56:57] op_sel_hi:[1,0]
	v_pk_mul_f32 v[8:9], v[54:55], v[8:9]
	s_waitcnt vmcnt(0)
	v_pk_mul_f32 v[10:11], v[12:13], v[10:11]
	v_rcp_f32_e32 v12, v1
	v_add_f32_e32 v1, 1.0, v3
	v_rcp_f32_e32 v13, v1
	v_pk_mul_f32 v[6:7], v[6:7], v[10:11]
	v_pk_mul_f32 v[10:11], v[16:17], v[56:57] op_sel_hi:[1,0]
	v_cvt_pk_bf16_f32 v5, v8, v9
	v_add_co_u32_e32 v8, vcc, 0x2200000, v50
	v_pk_mul_f32 v[10:11], v[14:15], v[10:11]
	v_pk_mul_f32 v[12:13], v[12:13], v[52:53]
	v_addc_co_u32_e32 v9, vcc, 0, v51, vcc
	v_pk_mul_f32 v[10:11], v[12:13], v[10:11]
	v_cmp_lt_i32_e32 vcc, s35, v0
	v_cvt_pk_bf16_f32 v6, v6, v7
	v_cvt_pk_bf16_f32 v7, v10, v11
	s_or_b64 s[6:7], vcc, s[6:7]
	global_store_dwordx4 v[8:9], v[4:7], off
	s_andn2_b64 exec, exec, s[6:7]
	s_cbranch_execnz .LBB0_743

; #define TIDX ((wv_ << 6) | lane_id_l())
; __device__ __forceinline__ unsigned pk2(float lo, float hi) { f32x2n v = {lo, hi}; bf16x2n b = __builtin_convertvector(v, bf16x2n); return __builtin_bit_cast(unsigned, b); }
; #define p (kparams())
; #define ws (kparams()->ws)
; __device__ __forceinline__ void norm_rows(const int wv_, KPR p, int l, int src_layer, const float* gvec, int part_shift, int part_scale, bool copy_ctx) {
;   const int wid = TIDX >> 6, lane = TIDX & 63;
;   const float* modl = (const float*)(p->ws + WS_MOD) + (size_t)l * 5 * 12288;
;   bf16_t* H = (bf16_t*)(p->ws + WS_H);
;   for (int row = blockIdx.x * 8 + wid; row < T; row += gridDim.x * 8) {
;     const float* x = xrow_ptr(p, src_layer, row);
;     const float* mw = modl + (size_t)row_who(row) * 12288;
;     f32x4 v[8]; float ss = 0.f;
; #pragma unroll
;     for (int j = 0; j < 8; ++j) { v[j] = *(const f32x4*)(x + lane * 4 + 256 * j); ss += v[j][0] * v[j][0] + v[j][1] * v[j][1] + v[j][2] * v[j][2] + v[j][3] * v[j][3]; }
;     const float rstd = rsqrtf(wave_sum(ss) * (1.f / D) + 1e-6f);
;     if (copy_ctx && row_who(row) == 4) { float* xd = xrow_dst(p, row);
; #pragma unroll
;       for (int j = 0; j < 8; ++j) *(f32x4*)(xd + lane * 4 + 256 * j) = v[j]; }
; #pragma unroll
;     for (int j = 0; j < 8; ++j) { const int c = lane * 4 + 256 * j;
;       const f32x4 g = *(const f32x4*)(gvec + c), sh = *(const f32x4*)(mw + part_shift * 2048 + c), sc = *(const f32x4*)(mw + part_scale * 2048 + c);
;       f32x4 o;
; #pragma unroll
;       for (int e = 0; e < 4; ++e) o[e] = v[j][e] * rstd * g[e] * (1.f + sc[e]) + sh[e];
;       u32x2 w; w.x = pk2(o[0], o[1]); w.y = pk2(o[2], o[3]);
;       *(u32x2*)(H + (size_t)row * D + c) = w; }
;   }
; }
.LBB0_1101:
	s_or_b64 exec, exec, s[8:9]
	s_mov_b64 s[8:9], s[0:1]
	s_mov_b64 s[16:17], s[0:1]
	s_waitcnt lgkmcnt(0)
	v_mov_b32_e32 v0, v153
	s_barrier
	v_readlane_b32 s10, v242, 2
	v_or_b32_e32 v0, s77, v0
	v_ashrrev_i32_e32 v0, 6, v0
	v_add_u32_e32 v0, s10, v0
	s_movk_i32 s10, 0x4400
	v_mov_b32_e32 v1, v153
	v_cmp_gt_i32_e32 vcc, s10, v0
	s_and_saveexec_b64 s[10:11], vcc
	s_cbranch_execz .LBB0_1108
	s_load_dwordx2 s[18:19], s[8:9], 0x118
	s_nop 0
	s_load_dwordx2 s[16:17], s[16:17], 0x38
	v_readlane_b32 s20, v242, 57
	v_lshlrev_b32_e32 v1, 2, v1
	v_readlane_b32 s21, v242, 58
	s_waitcnt lgkmcnt(0)
	s_add_u32 s12, s18, s12
	s_addc_u32 s13, s19, s13
	s_add_u32 s12, s12, 0x780000
	v_and_b32_e32 v4, 0xfc, v1
	s_addc_u32 s13, s13, 0
	s_lshl_b64 s[20:21], s[20:21], 2
	s_add_u32 s20, s16, s20
	v_or_b32_e32 v12, 0x400, v4
	s_addc_u32 s21, s17, s21
	v_lshlrev_b32_e32 v14, 2, v12
	v_mov_b32_e32 v15, v2
	v_lshl_add_u64 v[38:39], s[20:21], 0, v[14:15]
	v_or_b32_e32 v14, 0x500, v4
	v_lshlrev_b32_e32 v16, 2, v14
	v_mov_b32_e32 v17, v2
	v_lshl_add_u64 v[40:41], s[20:21], 0, v[16:17]
	v_or_b32_e32 v16, 0x600, v4
	v_lshlrev_b32_e32 v18, 2, v16
	v_mov_b32_e32 v19, v2
	v_lshl_add_u64 v[42:43], s[20:21], 0, v[18:19]
	v_or_b32_e32 v18, 0x700, v4
	v_lshlrev_b32_e32 v20, 2, v18
	v_mov_b32_e32 v21, v2
	s_add_u32 s16, s18, 0x7f8000
	v_lshlrev_b32_e32 v6, 2, v4
	v_mov_b32_e32 v7, v2
	v_lshl_add_u64 v[44:45], s[20:21], 0, v[20:21]
	v_lshlrev_b32_e32 v20, 1, v4
	s_addc_u32 s17, s19, 0
	v_lshl_add_u64 v[36:37], s[20:21], 0, v[6:7]
	v_or_b32_e32 v6, 0x100, v4
	v_or_b32_e32 v8, 0x200, v4
	v_or_b32_e32 v10, 0x300, v4
	v_lshl_add_u64 v[20:21], s[18:19], 0, v[20:21]
	s_mov_b64 s[18:19], 0x60e0000
	v_lshl_add_u64 v[46:47], v[20:21], 0, s[18:19]
	s_mov_b64 s[18:19], 0
	v_lshlrev_b32_e32 v48, 2, v4
	v_lshlrev_b32_e32 v50, 2, v6
	v_lshlrev_b32_e32 v52, 2, v8
	v_lshlrev_b32_e32 v54, 2, v10
	v_lshlrev_b32_e32 v56, 2, v12
	v_lshlrev_b32_e32 v58, 2, v14
	v_lshlrev_b32_e32 v60, 2, v16
	v_lshlrev_b32_e32 v62, 2, v18
	s_mov_b64 s[22:23], 0x1000
	v_lshl_add_u64 v[222:223], v[36:37], 0, s[22:23]
	global_load_dwordx4 v[88:91], v[36:37], off
	global_load_dwordx4 v[92:95], v[36:37], off offset:1024
	global_load_dwordx4 v[96:99], v[36:37], off offset:2048
	global_load_dwordx4 v[100:103], v[36:37], off offset:3072
	global_load_dwordx4 v[104:107], v[222:223], off
	global_load_dwordx4 v[108:111], v[222:223], off offset:1024
	global_load_dwordx4 v[112:115], v[222:223], off offset:2048
	global_load_dwordx4 v[116:119], v[222:223], off offset:3072
	s_branch .LBB0_1104
.LBB0_1103:
	s_or_b64 exec, exec, s[20:21]
	v_ashrrev_i32_e32 v5, 31, v4
	v_lshlrev_b64 v[4:5], 13, v[4:5]
	v_lshl_add_u64 v[4:5], v[6:7], 0, v[4:5]
	v_mov_b32_e32 v49, v2
	v_lshl_add_u64 v[4:5], v[4:5], 0, v[48:49]
	global_load_dwordx4 v[32:35], v[4:5], off
	global_load_dwordx4 v[28:31], v[4:5], off offset:1024
	global_load_dwordx4 v[24:27], v[4:5], off offset:2048
	global_load_dwordx4 v[20:23], v[4:5], off offset:3072
	v_add_co_u32_e32 v4, vcc, s52, v4
	s_mov_b64 s[20:21], 0x6000
	s_nop 0
	v_addc_co_u32_e32 v5, vcc, 0, v5, vcc
	global_load_dwordx4 v[16:19], v[4:5], off
	global_load_dwordx4 v[12:15], v[4:5], off offset:1024
	global_load_dwordx4 v[232:235], v[4:5], off offset:2048
	global_load_dwordx4 v[236:239], v[4:5], off offset:3072
	v_lshl_add_u64 v[66:67], s[12:13], 0, v[64:65]
	v_lshl_add_u64 v[68:69], v[66:67], 0, s[20:21]
	s_mov_b64 s[20:21], 0x8000
	v_lshl_add_u64 v[66:67], v[66:67], 0, s[20:21]
	v_lshl_add_u64 v[74:75], v[68:69], 0, v[48:49]
	v_lshl_add_u64 v[78:79], v[66:67], 0, v[48:49]
	s_mov_b64 s[22:23], 0x1000
	v_lshl_add_u64 v[224:225], v[78:79], 0, s[22:23]
	v_lshl_add_u64 v[226:227], v[74:75], 0, s[22:23]
	global_load_dwordx4 v[120:123], v[78:79], off
	global_load_dwordx4 v[190:193], v[74:75], off
	global_load_dwordx4 v[124:127], v[78:79], off offset:1024
	global_load_dwordx4 v[194:197], v[74:75], off offset:1024
	global_load_dwordx4 v[128:131], v[78:79], off offset:2048
	global_load_dwordx4 v[198:201], v[74:75], off offset:2048
	global_load_dwordx4 v[132:135], v[78:79], off offset:3072
	global_load_dwordx4 v[202:205], v[74:75], off offset:3072
	global_load_dwordx4 v[136:139], v[224:225], off
	global_load_dwordx4 v[206:209], v[226:227], off
	global_load_dwordx4 v[140:143], v[224:225], off offset:1024
	global_load_dwordx4 v[210:213], v[226:227], off offset:1024
	global_load_dwordx4 v[144:147], v[224:225], off offset:2048
	global_load_dwordx4 v[214:217], v[226:227], off offset:2048
	global_load_dwordx4 v[148:151], v[224:225], off offset:3072
	global_load_dwordx4 v[218:221], v[226:227], off offset:3072
	v_mov_b32_e32 v51, v2
	v_mov_b32_e32 v53, v2
	v_mov_b32_e32 v55, v2
	v_mov_b32_e32 v57, v2
	v_mov_b32_e32 v59, v2
	v_mov_b32_e32 v61, v2
	v_mov_b32_e32 v63, v2
	s_waitcnt vmcnt(23)
	v_mul_f32_e32 v1, v33, v33
	s_waitcnt vmcnt(22)
	v_mul_f32_e32 v3, v29, v29
	v_fmac_f32_e32 v1, v32, v32
	v_fmac_f32_e32 v3, v28, v28
	v_fmac_f32_e32 v1, v34, v34
	v_fmac_f32_e32 v3, v30, v30
	v_fmac_f32_e32 v1, v35, v35
	v_fmac_f32_e32 v3, v31, v31
	v_add_f32_e32 v1, v1, v3
	s_waitcnt vmcnt(21)
	v_mul_f32_e32 v3, v25, v25
	v_fmac_f32_e32 v3, v24, v24
	v_fmac_f32_e32 v3, v26, v26
	v_fmac_f32_e32 v3, v27, v27
	v_add_f32_e32 v1, v1, v3
	s_waitcnt vmcnt(20)
	v_mul_f32_e32 v3, v21, v21
	s_waitcnt vmcnt(19)
	v_mov_b32_e32 v8, v17
	s_waitcnt vmcnt(18)
	v_mov_b32_e32 v9, v13
	v_fmac_f32_e32 v3, v20, v20
	v_mov_b32_e32 v6, v16
	v_mov_b32_e32 v7, v12
	v_pk_mul_f32 v[8:9], v[8:9], v[8:9]
	v_fmac_f32_e32 v3, v22, v22
	v_pk_fma_f32 v[6:7], v[6:7], v[6:7], v[8:9]
	v_mov_b32_e32 v8, v18
	v_mov_b32_e32 v9, v14
	v_fmac_f32_e32 v3, v23, v23
	v_pk_fma_f32 v[6:7], v[8:9], v[8:9], v[6:7]
	v_mov_b32_e32 v8, v19
	v_mov_b32_e32 v9, v15
	v_add_f32_e32 v1, v1, v3
	v_pk_fma_f32 v[6:7], v[8:9], v[8:9], v[6:7]
	s_nop 0
	v_add_f32_e32 v1, v1, v6
	v_add_f32_e32 v1, v1, v7
	s_waitcnt vmcnt(17)
; __device__ __forceinline__ unsigned pk2(float lo, float hi) { f32x2n v = {lo, hi}; bf16x2n b = __builtin_convertvector(v, bf16x2n); return __builtin_bit_cast(unsigned, b); }
; #define p (kparams())
; __device__ __forceinline__ void norm_rows(const int wv_, KPR p, int l, int src_layer, const float* gvec, int part_shift, int part_scale, bool copy_ctx) {
;     ...
;     f32x4 v[8]; float ss = 0.f;
; #pragma unroll
;     for (int j = 0; j < 8; ++j) { v[j] = *(const f32x4*)(x + lane * 4 + 256 * j); ss += v[j][0] * v[j][0] + v[j][1] * v[j][1] + v[j][2] * v[j][2] + v[j][3] * v[j][3]; }
;     const float rstd = rsqrtf(wave_sum(ss) * (1.f / D) + 1e-6f);
;     if (copy_ctx && row_who(row) == 4) { float* xd = xrow_dst(p, row);
; #pragma unroll
;       for (int j = 0; j < 8; ++j) *(f32x4*)(xd + lane * 4 + 256 * j) = v[j]; }
; #pragma unroll
;     for (int j = 0; j < 8; ++j) { const int c = lane * 4 + 256 * j;
;       const f32x4 g = *(const f32x4*)(gvec + c), sh = *(const f32x4*)(mw + part_shift * 2048 + c), sc = *(const f32x4*)(mw + part_scale * 2048 + c);
;       f32x4 o;
; #pragma unroll
;       for (int e = 0; e < 4; ++e) o[e] = v[j][e] * rstd * g[e] * (1.f + sc[e]) + sh[e];
;       u32x2 w; w.x = pk2(o[0], o[1]); w.y = pk2(o[2], o[3]);
;       *(u32x2*)(H + (size_t)row * D + c) = w; }
	v_mov_b32_e32 v68, v233
	s_waitcnt vmcnt(16)
	v_mov_b32_e32 v69, v237
	v_mov_b32_e32 v66, v232
	v_mov_b32_e32 v67, v236
	v_pk_mul_f32 v[68:69], v[68:69], v[68:69]
	v_pk_fma_f32 v[66:67], v[66:67], v[66:67], v[68:69]
	v_mov_b32_e32 v68, v234
	v_mov_b32_e32 v69, v238
	v_pk_fma_f32 v[66:67], v[68:69], v[68:69], v[66:67]
	v_mov_b32_e32 v68, v235
	v_mov_b32_e32 v69, v239
	v_pk_fma_f32 v[66:67], v[68:69], v[68:69], v[66:67]
	s_nop 0
	v_add_f32_e32 v1, v1, v66
	v_add_f32_e32 v1, v1, v67
	ds_bpermute_b32 v3, v170, v1
	s_waitcnt lgkmcnt(0)
	v_add_f32_e32 v1, v1, v3
	ds_bpermute_b32 v3, v171, v1
	s_waitcnt lgkmcnt(0)
	v_add_f32_e32 v1, v1, v3
	ds_bpermute_b32 v3, v172, v1
	s_waitcnt lgkmcnt(0)
	v_add_f32_e32 v1, v1, v3
	ds_bpermute_b32 v3, v173, v1
	s_waitcnt lgkmcnt(0)
	v_add_f32_e32 v1, v1, v3
	ds_bpermute_b32 v3, v174, v1
	s_waitcnt lgkmcnt(0)
	v_add_f32_e32 v1, v1, v3
	ds_bpermute_b32 v3, v175, v1
	s_waitcnt lgkmcnt(0)
	v_add_f32_e32 v1, v1, v3
	v_fmamk_f32 v1, v1, 0x3a000000, v152
	v_cmp_gt_f32_e32 vcc, s96, v1
	v_mul_f32_e32 v3, 0x4b800000, v1
	s_nop 0
	v_cndmask_b32_e32 v1, v1, v3, vcc
	v_rsq_f32_e32 v1, v1
	s_nop 0
	v_mul_f32_e32 v3, 0x45800000, v1
	v_cndmask_b32_e32 v64, v1, v3, vcc
	v_pk_mul_f32 v[32:33], v[32:33], v[64:65] op_sel_hi:[1,0]
	v_pk_mul_f32 v[34:35], v[34:35], v[64:65] op_sel_hi:[1,0]
	v_pk_mul_f32 v[28:29], v[28:29], v[64:65] op_sel_hi:[1,0]
	v_pk_mul_f32 v[30:31], v[30:31], v[64:65] op_sel_hi:[1,0]
	v_pk_mul_f32 v[24:25], v[24:25], v[64:65] op_sel_hi:[1,0]
	v_pk_mul_f32 v[26:27], v[26:27], v[64:65] op_sel_hi:[1,0]
	v_pk_mul_f32 v[20:21], v[20:21], v[64:65] op_sel_hi:[1,0]
	v_pk_mul_f32 v[22:23], v[22:23], v[64:65] op_sel_hi:[1,0]
	v_pk_mul_f32 v[16:17], v[16:17], v[64:65] op_sel_hi:[1,0]
	v_pk_mul_f32 v[18:19], v[18:19], v[64:65] op_sel_hi:[1,0]
	v_pk_mul_f32 v[12:13], v[12:13], v[64:65] op_sel_hi:[1,0]
	v_pk_mul_f32 v[14:15], v[14:15], v[64:65] op_sel_hi:[1,0]
	v_pk_mul_f32 v[232:233], v[232:233], v[64:65] op_sel_hi:[1,0]
	v_pk_mul_f32 v[234:235], v[234:235], v[64:65] op_sel_hi:[1,0]
	v_pk_mul_f32 v[236:237], v[236:237], v[64:65] op_sel_hi:[1,0]
	v_pk_mul_f32 v[238:239], v[238:239], v[64:65] op_sel_hi:[1,0]
	v_ashrrev_i32_e32 v1, 31, v0
	v_lshlrev_b64 v[82:83], 12, v[0:1]
	v_lshl_add_u64 v[70:71], v[46:47], 0, v[82:83]
	v_add_u32_e32 v0, s73, v0
	v_cmp_lt_i32_e32 vcc, s38, v0
	s_or_b64 s[18:19], vcc, s[18:19]
	s_waitcnt vmcnt(14)
	v_pk_mul_f32 v[32:33], v[88:89], v[32:33]
	v_pk_mul_f32 v[34:35], v[90:91], v[34:35]
	v_pk_add_f32 v[228:229], v[120:121], 1.0 op_sel_hi:[1,0]
	v_pk_add_f32 v[230:231], v[122:123], 1.0 op_sel_hi:[1,0]
	v_pk_fma_f32 v[32:33], v[228:229], v[32:33], v[190:191]
	v_pk_fma_f32 v[34:35], v[230:231], v[34:35], v[192:193]
	v_cvt_pk_bf16_f32 v32, v32, v33
	v_cvt_pk_bf16_f32 v33, v34, v35
	global_store_dwordx2 v[70:71], v[32:33], off
	s_waitcnt vmcnt(13)
	v_pk_mul_f32 v[28:29], v[92:93], v[28:29]
	v_pk_mul_f32 v[30:31], v[94:95], v[30:31]
	v_pk_add_f32 v[228:229], v[124:125], 1.0 op_sel_hi:[1,0]
	v_pk_add_f32 v[230:231], v[126:127], 1.0 op_sel_hi:[1,0]
	v_pk_fma_f32 v[28:29], v[228:229], v[28:29], v[194:195]
	v_pk_fma_f32 v[30:31], v[230:231], v[30:31], v[196:197]
	v_cvt_pk_bf16_f32 v28, v28, v29
	v_cvt_pk_bf16_f32 v29, v30, v31
	global_store_dwordx2 v[70:71], v[28:29], off offset:512
	s_waitcnt vmcnt(12)
	v_pk_mul_f32 v[24:25], v[96:97], v[24:25]
	v_pk_mul_f32 v[26:27], v[98:99], v[26:27]
	v_pk_add_f32 v[228:229], v[128:129], 1.0 op_sel_hi:[1,0]
	v_pk_add_f32 v[230:231], v[130:131], 1.0 op_sel_hi:[1,0]
	v_pk_fma_f32 v[24:25], v[228:229], v[24:25], v[198:199]
	v_pk_fma_f32 v[26:27], v[230:231], v[26:27], v[200:201]
	v_cvt_pk_bf16_f32 v24, v24, v25
	v_cvt_pk_bf16_f32 v25, v26, v27
	global_store_dwordx2 v[70:71], v[24:25], off offset:1024
	s_waitcnt vmcnt(11)
	v_pk_mul_f32 v[20:21], v[100:101], v[20:21]
	v_pk_mul_f32 v[22:23], v[102:103], v[22:23]
	v_pk_add_f32 v[228:229], v[132:133], 1.0 op_sel_hi:[1,0]
	v_pk_add_f32 v[230:231], v[134:135], 1.0 op_sel_hi:[1,0]
	v_pk_fma_f32 v[20:21], v[228:229], v[20:21], v[202:203]
	v_pk_fma_f32 v[22:23], v[230:231], v[22:23], v[204:205]
	v_cvt_pk_bf16_f32 v20, v20, v21
	v_cvt_pk_bf16_f32 v21, v22, v23
	global_store_dwordx2 v[70:71], v[20:21], off offset:1536
	s_waitcnt vmcnt(10)
	v_pk_mul_f32 v[16:17], v[104:105], v[16:17]
	v_pk_mul_f32 v[18:19], v[106:107], v[18:19]
	v_pk_add_f32 v[228:229], v[136:137], 1.0 op_sel_hi:[1,0]
	v_pk_add_f32 v[230:231], v[138:139], 1.0 op_sel_hi:[1,0]
	v_pk_fma_f32 v[16:17], v[228:229], v[16:17], v[206:207]
	v_pk_fma_f32 v[18:19], v[230:231], v[18:19], v[208:209]
	v_cvt_pk_bf16_f32 v16, v16, v17
	v_cvt_pk_bf16_f32 v17, v18, v19
	global_store_dwordx2 v[70:71], v[16:17], off offset:2048
	s_waitcnt vmcnt(9)
	v_pk_mul_f32 v[12:13], v[108:109], v[12:13]
	v_pk_mul_f32 v[14:15], v[110:111], v[14:15]
	v_pk_add_f32 v[228:229], v[140:141], 1.0 op_sel_hi:[1,0]
	v_pk_add_f32 v[230:231], v[142:143], 1.0 op_sel_hi:[1,0]
	v_pk_fma_f32 v[12:13], v[228:229], v[12:13], v[210:211]
	v_pk_fma_f32 v[14:15], v[230:231], v[14:15], v[212:213]
	v_cvt_pk_bf16_f32 v12, v12, v13
	v_cvt_pk_bf16_f32 v13, v14, v15
	global_store_dwordx2 v[70:71], v[12:13], off offset:2560
	s_waitcnt vmcnt(8)
	v_pk_mul_f32 v[232:233], v[112:113], v[232:233]
	v_pk_mul_f32 v[234:235], v[114:115], v[234:235]
	v_pk_add_f32 v[228:229], v[144:145], 1.0 op_sel_hi:[1,0]
	v_pk_add_f32 v[230:231], v[146:147], 1.0 op_sel_hi:[1,0]
	v_pk_fma_f32 v[232:233], v[228:229], v[232:233], v[214:215]
	v_pk_fma_f32 v[234:235], v[230:231], v[234:235], v[216:217]
	v_cvt_pk_bf16_f32 v232, v232, v233
	v_cvt_pk_bf16_f32 v233, v234, v235
	global_store_dwordx2 v[70:71], v[232:233], off offset:3072
	s_waitcnt vmcnt(7)
	v_pk_mul_f32 v[236:237], v[116:117], v[236:237]
	v_pk_mul_f32 v[238:239], v[118:119], v[238:239]
	v_pk_add_f32 v[228:229], v[148:149], 1.0 op_sel_hi:[1,0]
	v_pk_add_f32 v[230:231], v[150:151], 1.0 op_sel_hi:[1,0]
	v_pk_fma_f32 v[236:237], v[228:229], v[236:237], v[218:219]
	v_pk_fma_f32 v[238:239], v[230:231], v[238:239], v[220:221]
	v_cvt_pk_bf16_f32 v236, v236, v237
	v_cvt_pk_bf16_f32 v237, v238, v239
	global_store_dwordx2 v[70:71], v[236:237], off offset:3584
	s_andn2_b64 exec, exec, s[18:19]
	s_cbranch_execz .LBB0_1108
